# tail: wave reductions of the sample-attention combine via DPP/permlane swaps instead of ds_bpermute
# baseline (speedup 1.0000x reference)
.LBB0_1468:
	v_readfirstlane_b32 s0, v0
	v_mov_b32_e32 v1, v0
	s_lshr_b32 s0, s0, 6
	v_readlane_b32 s60, v254, 22
	s_add_i32 s22, s0, s60
	s_ashr_i32 s24, s22, 5
	s_and_b32 s10, s0, 3
	s_lshl_b32 s0, s24, 2
	s_add_i32 s12, s0, 0x4100
	s_bfe_u32 s11, s22, 0x30002
	s_ashr_i32 s13, s12, 31
	s_add_u32 s6, s72, 0x3000000
	s_addc_u32 s7, s73, 0
	s_add_u32 s2, s72, 0x4100000
	s_addc_u32 s3, s73, 0
	s_add_u32 s4, s72, 0x5200000
	s_addc_u32 s5, s73, 0
	s_add_u32 s8, s72, 0x6300000
	s_addc_u32 s9, s73, 0
	s_add_u32 s20, s72, 0xde00000
	s_addc_u32 s21, s73, 0
	s_or_b32 s0, s12, s10
	s_mov_b32 s1, s13
	s_lshl_b64 s[0:1], s[0:1], 9
	s_lshl_b32 s18, s11, 6
	v_and_b32_e32 v1, 63, v1
	s_or_b32 s0, s0, s18
	v_or_b32_e32 v2, s0, v1
	v_mov_b32_e32 v3, s1
	s_lshl_b32 s0, s11, 2
	v_readlane_b32 s1, v254, 24
	s_add_u32 s19, s1, s0
	v_readlane_b32 s0, v254, 25
	s_addc_u32 s23, s0, 0
	s_lshl_b64 s[0:1], s[12:13], 9
	v_or_b32_e32 v6, s0, v1
	v_mov_b32_e32 v7, s1
	s_lshl_b64 s[0:1], s[12:13], 5
	s_add_u32 s14, s19, s0
	s_addc_u32 s15, s23, s1
	s_or_b32 s0, s12, 1
	s_mov_b32 s1, s13
	s_lshl_b64 s[16:17], s[0:1], 9
	s_lshl_b64 s[0:1], s[0:1], 5
	s_add_u32 s0, s19, s0
	v_or_b32_e32 v10, s16, v1
	v_mov_b32_e32 v11, s17
	s_addc_u32 s1, s23, s1
	s_or_b32 s16, s12, 2
	s_mov_b32 s17, s13
	s_lshl_b64 s[26:27], s[16:17], 9
	v_or_b32_e32 v14, s26, v1
	v_lshlrev_b64 v[2:3], 1, v[2:3]
	v_or_b32_e32 v6, s18, v6
	v_or_b32_e32 v10, s18, v10
	v_or_b32_e32 v14, s18, v14
	v_mov_b32_e32 v15, s27
	v_lshl_add_u64 v[4:5], s[6:7], 0, v[2:3]
	v_lshl_add_u64 v[2:3], s[8:9], 0, v[2:3]
	v_lshlrev_b64 v[8:9], 1, v[6:7]
	v_lshlrev_b64 v[12:13], 1, v[10:11]
	v_lshlrev_b64 v[16:17], 1, v[14:15]
	v_lshl_add_u64 v[6:7], s[2:3], 0, v[8:9]
	v_lshl_add_u64 v[8:9], s[4:5], 0, v[8:9]
	v_lshl_add_u64 v[10:11], s[2:3], 0, v[12:13]
	v_lshl_add_u64 v[12:13], s[4:5], 0, v[12:13]
	v_lshl_add_u64 v[14:15], s[2:3], 0, v[16:17]
	v_lshl_add_u64 v[16:17], s[4:5], 0, v[16:17]
	global_load_ushort v18, v[2:3], off
	global_load_ushort v19, v[6:7], off
	global_load_ushort v20, v[10:11], off
	global_load_ushort v21, v[14:15], off
	global_load_ushort v22, v[16:17], off
	global_load_ushort v23, v[12:13], off
	global_load_ushort v24, v[8:9], off
	global_load_ushort v25, v[4:5], off
	v_mov_b32_e32 v3, 0
	global_load_dword v13, v3, s[14:15]
	s_lshl_b64 s[14:15], s[16:17], 5
	s_add_u32 s14, s19, s14
	s_addc_u32 s15, s23, s15
	s_or_b32 s12, s12, 3
	s_lshl_b64 s[16:17], s[12:13], 9
	s_lshl_b64 s[12:13], s[12:13], 5
	s_add_u32 s12, s19, s12
	v_lshlrev_b32_e32 v2, 2, v1
	s_addc_u32 s13, s23, s13
	s_mov_b64 s[26:27], 0xdf00000
	v_lshl_add_u64 v[4:5], s[72:73], 0, v[2:3]
	s_add_u32 s25, s72, 0xdd00000
	v_lshl_add_u64 v[14:15], v[4:5], 0, s[26:27]
	v_or_b32_e32 v2, s16, v1
	s_addc_u32 s26, s73, 0
	s_lshl_b32 s16, s24, 4
	v_mov_b32_e32 v5, s17
	s_ashr_i32 s17, s16, 31
	s_and_b32 s27, s22, 31
	s_lshl_b64 s[28:29], s[16:17], 5
	s_or_b32 s28, s28, s27
	s_lshl_b64 s[30:31], s[28:29], 2
	s_add_u32 s34, s25, s30
	v_or_b32_e32 v4, s18, v2
	s_addc_u32 s35, s26, s31
	v_lshlrev_b64 v[4:5], 1, v[4:5]
	s_add_u32 s30, s20, s30
	v_lshl_add_u64 v[6:7], s[2:3], 0, v[4:5]
	s_addc_u32 s31, s21, s31
	s_lshl_b64 s[28:29], s[28:29], 8
	v_lshl_add_u64 v[8:9], s[4:5], 0, v[4:5]
	global_load_ushort v5, v[6:7], off
	v_lshl_add_u64 v[6:7], v[14:15], 0, s[28:29]
	s_or_b32 s28, s16, 1
	s_ashr_i32 s29, s28, 31
	s_lshl_b64 s[28:29], s[28:29], 5
	s_or_b32 s28, s28, s27
	s_lshl_b64 s[36:37], s[28:29], 2
	s_add_u32 s38, s25, s36
	s_addc_u32 s39, s26, s37
	s_add_u32 s36, s20, s36
	s_addc_u32 s37, s21, s37
	s_lshl_b64 s[28:29], s[28:29], 8
	v_lshl_add_u64 v[10:11], v[14:15], 0, s[28:29]
	s_or_b32 s28, s16, 2
	s_ashr_i32 s29, s28, 31
	s_lshl_b64 s[28:29], s[28:29], 5
	s_or_b32 s28, s28, s27
	s_lshl_b64 s[40:41], s[28:29], 2
	s_add_u32 s42, s25, s40
	s_addc_u32 s43, s26, s41
	s_add_u32 s40, s20, s40
	s_addc_u32 s41, s21, s41
	s_lshl_b64 s[28:29], s[28:29], 8
	v_lshl_add_u64 v[16:17], v[14:15], 0, s[28:29]
	s_or_b32 s28, s16, 3
	s_ashr_i32 s29, s28, 31
	s_lshl_b64 s[28:29], s[28:29], 5
	s_or_b32 s28, s28, s27
	s_lshl_b64 s[44:45], s[28:29], 2
	s_add_u32 s46, s25, s44
	s_addc_u32 s47, s26, s45
	s_add_u32 s44, s20, s44
	s_addc_u32 s45, s21, s45
	s_lshl_b64 s[28:29], s[28:29], 8
	s_mov_b32 s11, 0
	s_waitcnt vmcnt(9)
	v_lshlrev_b32_e32 v4, 16, v18
	s_waitcnt vmcnt(8)
	v_lshlrev_b32_e32 v103, 16, v19
	v_lshl_add_u64 v[18:19], v[14:15], 0, s[28:29]
	s_or_b32 s28, s16, 4
	s_ashr_i32 s29, s28, 31
	s_lshl_b64 s[28:29], s[28:29], 5
	s_or_b32 s28, s28, s27
	s_lshl_b64 s[48:49], s[28:29], 2
	s_add_u32 s50, s25, s48
	s_addc_u32 s51, s26, s49
	s_add_u32 s48, s20, s48
	s_addc_u32 s49, s21, s49
	s_lshl_b64 s[28:29], s[28:29], 8
	s_waitcnt vmcnt(7)
	v_lshlrev_b32_e32 v92, 16, v20
	s_waitcnt vmcnt(6)
	v_lshlrev_b32_e32 v12, 16, v21
	v_lshl_add_u64 v[20:21], v[14:15], 0, s[28:29]
	s_or_b32 s28, s16, 5
	s_ashr_i32 s29, s28, 31
	s_lshl_b64 s[28:29], s[28:29], 5
	s_or_b32 s28, s28, s27
	s_lshl_b64 s[52:53], s[28:29], 2
	s_add_u32 s54, s25, s52
	s_addc_u32 s55, s26, s53
	s_add_u32 s52, s20, s52
	s_addc_u32 s53, s21, s53
	s_lshl_b64 s[28:29], s[28:29], 8
	v_lshl_add_u64 v[26:27], v[14:15], 0, s[28:29]
	s_or_b32 s28, s16, 6
	s_ashr_i32 s29, s28, 31
	s_lshl_b64 s[28:29], s[28:29], 5
	s_or_b32 s28, s28, s27
	global_load_dword v79, v[6:7], off
	global_load_dword v74, v[10:11], off
	global_load_dword v69, v[16:17], off
	global_load_dword v68, v[18:19], off
	global_load_dword v66, v[20:21], off
	global_load_dword v61, v[26:27], off
	global_load_ushort v6, v[8:9], off
	global_load_dword v89, v3, s[34:35]
	global_load_dword v93, v3, s[30:31]
	global_load_dword v86, v3, s[38:39]
	global_load_dword v88, v3, s[36:37]
	global_load_dword v80, v3, s[42:43]
	global_load_dword v82, v3, s[40:41]
	global_load_dword v75, v3, s[46:47]
	global_load_dword v77, v3, s[44:45]
	s_lshl_b64 s[30:31], s[28:29], 2
	s_add_u32 s34, s25, s30
	s_addc_u32 s35, s26, s31
	s_add_u32 s30, s20, s30
	s_addc_u32 s31, s21, s31
	s_lshl_b64 s[28:29], s[28:29], 8
	v_lshl_add_u64 v[8:9], v[14:15], 0, s[28:29]
	s_or_b32 s28, s16, 7
	s_ashr_i32 s29, s28, 31
	s_lshl_b64 s[28:29], s[28:29], 5
	s_or_b32 s28, s28, s27
	s_lshl_b64 s[36:37], s[28:29], 2
	s_add_u32 s38, s25, s36
	s_addc_u32 s39, s26, s37
	s_add_u32 s36, s20, s36
	s_addc_u32 s37, s21, s37
	s_lshl_b64 s[28:29], s[28:29], 8
	v_lshl_add_u64 v[10:11], v[14:15], 0, s[28:29]
	s_or_b32 s28, s16, 8
	s_ashr_i32 s29, s28, 31
	s_lshl_b64 s[28:29], s[28:29], 5
	s_or_b32 s28, s28, s27
	global_load_dword v85, v3, s[50:51]
	global_load_dword v87, v3, s[48:49]
	global_load_dword v78, v3, s[54:55]
	global_load_dword v81, v3, s[52:53]
	global_load_dword v73, v3, s[34:35]
	global_load_dword v76, v3, s[30:31]
	global_load_dword v70, v3, s[38:39]
	global_load_dword v71, v3, s[36:37]
	s_lshl_b64 s[30:31], s[28:29], 2
	s_add_u32 s34, s25, s30
	s_addc_u32 s35, s26, s31
	s_add_u32 s30, s20, s30
	s_addc_u32 s31, s21, s31
	s_lshl_b64 s[28:29], s[28:29], 8
	v_lshl_add_u64 v[16:17], v[14:15], 0, s[28:29]
	s_or_b32 s28, s16, 9
	s_ashr_i32 s29, s28, 31
	s_lshl_b64 s[28:29], s[28:29], 5
	s_or_b32 s28, s28, s27
	s_lshl_b64 s[36:37], s[28:29], 2
	s_add_u32 s38, s25, s36
	s_addc_u32 s39, s26, s37
	s_add_u32 s36, s20, s36
	s_addc_u32 s37, s21, s37
	s_lshl_b64 s[28:29], s[28:29], 8
	v_lshl_add_u64 v[18:19], v[14:15], 0, s[28:29]
	s_or_b32 s28, s16, 10
	s_ashr_i32 s29, s28, 31
	s_lshl_b64 s[28:29], s[28:29], 5
	s_or_b32 s28, s28, s27
	s_lshl_b64 s[40:41], s[28:29], 2
	s_add_u32 s42, s25, s40
	s_addc_u32 s43, s26, s41
	s_add_u32 s40, s20, s40
	s_addc_u32 s41, s21, s41
	s_lshl_b64 s[28:29], s[28:29], 8
	v_lshl_add_u64 v[20:21], v[14:15], 0, s[28:29]
	s_or_b32 s28, s16, 11
	s_ashr_i32 s29, s28, 31
	s_lshl_b64 s[28:29], s[28:29], 5
	s_or_b32 s28, s28, s27
	s_lshl_b64 s[44:45], s[28:29], 2
	s_add_u32 s46, s25, s44
	s_addc_u32 s47, s26, s45
	s_add_u32 s44, s20, s44
	s_addc_u32 s45, s21, s45
	s_lshl_b64 s[28:29], s[28:29], 8
	v_lshl_add_u64 v[26:27], v[14:15], 0, s[28:29]
	s_or_b32 s28, s16, 12
	s_ashr_i32 s29, s28, 31
	s_lshl_b64 s[28:29], s[28:29], 5
	s_or_b32 s28, s28, s27
	global_load_dword v98, v3, s[34:35]
	global_load_dword v99, v3, s[30:31]
	global_load_dword v95, v3, s[38:39]
	global_load_dword v96, v3, s[36:37]
	global_load_dword v90, v3, s[42:43]
	global_load_dword v91, v3, s[40:41]
	global_load_dword v83, v3, s[46:47]
	global_load_dword v84, v3, s[44:45]
	s_lshl_b64 s[30:31], s[28:29], 2
	s_add_u32 s34, s25, s30
	s_addc_u32 s35, s26, s31
	s_add_u32 s30, s20, s30
	s_addc_u32 s31, s21, s31
	s_lshl_b64 s[28:29], s[28:29], 8
	v_lshl_add_u64 v[28:29], v[14:15], 0, s[28:29]
	s_or_b32 s28, s16, 13
	s_ashr_i32 s29, s28, 31
	s_lshl_b64 s[28:29], s[28:29], 5
	s_or_b32 s28, s28, s27
	s_lshl_b64 s[36:37], s[28:29], 2
	s_add_u32 s38, s25, s36
	s_addc_u32 s39, s26, s37
	s_add_u32 s36, s20, s36
	s_addc_u32 s37, s21, s37
	s_lshl_b64 s[28:29], s[28:29], 8
	v_lshl_add_u64 v[30:31], v[14:15], 0, s[28:29]
	s_or_b32 s28, s16, 14
	s_ashr_i32 s29, s28, 31
	s_lshl_b64 s[28:29], s[28:29], 5
	s_or_b32 s28, s28, s27
	s_lshl_b64 s[40:41], s[28:29], 2
	s_add_u32 s42, s25, s40
	s_addc_u32 s43, s26, s41
	s_add_u32 s40, s20, s40
	s_addc_u32 s41, s21, s41
	s_or_b32 s16, s16, 15
	s_ashr_i32 s17, s16, 31
	s_lshl_b64 s[16:17], s[16:17], 5
	s_lshl_b64 s[28:29], s[28:29], 8
	s_or_b32 s16, s16, s27
	global_load_dword v120, v[8:9], off
	global_load_dword v118, v[10:11], off
	global_load_dword v114, v[16:17], off
	global_load_dword v111, v[18:19], off
	global_load_dword v104, v[20:21], off
	global_load_dword v100, v[26:27], off
	global_load_dword v97, v[28:29], off
	global_load_dword v94, v[30:31], off
	v_lshl_add_u64 v[16:17], v[14:15], 0, s[28:29]
	s_lshl_b64 s[28:29], s[16:17], 2
	s_add_u32 s44, s25, s28
	s_addc_u32 s45, s26, s29
	s_add_u32 s28, s20, s28
	s_addc_u32 s29, s21, s29
	s_add_i32 s24, s22, 0x800
	s_lshl_b64 s[16:17], s[16:17], 8
	s_ashr_i32 s33, s24, 5
	v_lshl_add_u64 v[18:19], v[14:15], 0, s[16:17]
	s_lshl_b32 s16, s33, 2
	s_addk_i32 s16, 0x4100
	s_ashr_i32 s17, s16, 31
	global_load_dword v115, v3, s[34:35]
	global_load_dword v116, v3, s[30:31]
	global_load_dword v112, v3, s[38:39]
	global_load_dword v113, v3, s[36:37]
	global_load_dword v109, v3, s[42:43]
	global_load_dword v110, v3, s[40:41]
	global_load_dword v101, v3, s[44:45]
	global_load_dword v102, v3, s[28:29]
	s_or_b32 s28, s16, s10
	s_mov_b32 s29, s17
	s_lshl_b64 s[28:29], s[28:29], 9
	s_or_b32 s28, s28, s18
	v_or_b32_e32 v8, s28, v1
	v_mov_b32_e32 v9, s29
	v_lshlrev_b64 v[8:9], 1, v[8:9]
	v_lshl_add_u64 v[20:21], s[6:7], 0, v[8:9]
	s_lshl_b64 s[6:7], s[16:17], 9
	s_waitcnt vmcnt(47)
	v_lshlrev_b32_e32 v117, 16, v5
	v_lshl_add_u64 v[26:27], s[8:9], 0, v[8:9]
	v_or_b32_e32 v5, s6, v1
	v_mov_b32_e32 v9, s7
	s_lshl_b64 s[6:7], s[16:17], 5
	s_add_u32 s6, s19, s6
	s_addc_u32 s7, s23, s7
	s_or_b32 s8, s16, 1
	s_mov_b32 s9, s17
	v_or_b32_e32 v8, s18, v5
	s_lshl_b64 s[28:29], s[8:9], 9
	s_lshl_b64 s[8:9], s[8:9], 5
	v_lshlrev_b64 v[8:9], 1, v[8:9]
	s_add_u32 s8, s19, s8
	v_lshl_add_u64 v[28:29], s[2:3], 0, v[8:9]
	v_lshl_add_u64 v[30:31], s[4:5], 0, v[8:9]
	v_or_b32_e32 v5, s28, v1
	v_mov_b32_e32 v9, s29
	s_addc_u32 s9, s23, s9
	s_or_b32 s28, s16, 2
	s_mov_b32 s29, s17
	s_lshl_b64 s[30:31], s[28:29], 9
	s_lshl_b64 s[28:29], s[28:29], 5
	v_or_b32_e32 v8, s18, v5
	s_add_u32 s28, s19, s28
	v_lshlrev_b64 v[8:9], 1, v[8:9]
	v_or_b32_e32 v5, s30, v1
	s_addc_u32 s29, s23, s29
	s_or_b32 s16, s16, 3
	v_lshl_add_u64 v[32:33], s[2:3], 0, v[8:9]
	v_lshl_add_u64 v[34:35], s[4:5], 0, v[8:9]
	global_load_dword v122, v[16:17], off
	global_load_dword v121, v[18:19], off
	global_load_ushort v64, v[20:21], off
	global_load_ushort v10, v[26:27], off
	global_load_ushort v65, v[28:29], off
	global_load_ushort v55, v[30:31], off
	global_load_ushort v56, v[32:33], off
	global_load_ushort v8, v[34:35], off
	v_or_b32_e32 v16, s18, v5
	v_mov_b32_e32 v17, s31
	s_lshl_b64 s[30:31], s[16:17], 9
	v_lshlrev_b64 v[16:17], 1, v[16:17]
	v_or_b32_e32 v5, s30, v1
	v_lshl_add_u64 v[28:29], s[2:3], 0, v[16:17]
	v_lshl_add_u64 v[30:31], s[4:5], 0, v[16:17]
	v_or_b32_e32 v16, s18, v5
	v_mov_b32_e32 v17, s31
	v_lshlrev_b64 v[16:17], 1, v[16:17]
	v_lshl_add_u64 v[34:35], s[2:3], 0, v[16:17]
	s_lshl_b64 s[2:3], s[16:17], 5
	v_lshl_add_u64 v[36:37], s[4:5], 0, v[16:17]
	s_add_u32 s4, s19, s2
	s_addc_u32 s5, s23, s3
	s_lshl_b32 s2, s33, 4
	s_ashr_i32 s3, s2, 31
	s_lshl_b64 s[16:17], s[2:3], 5
	s_or_b32 s16, s16, s27
	s_lshl_b64 s[18:19], s[16:17], 2
	s_add_u32 s30, s25, s18
	s_addc_u32 s31, s26, s19
	s_add_u32 s18, s20, s18
	s_addc_u32 s19, s21, s19
	s_lshl_b64 s[16:17], s[16:17], 8
	v_lshl_add_u64 v[38:39], v[14:15], 0, s[16:17]
	s_or_b32 s16, s2, 1
	s_ashr_i32 s17, s16, 31
	s_lshl_b64 s[16:17], s[16:17], 5
	s_or_b32 s16, s16, s27
	s_lshl_b64 s[34:35], s[16:17], 2
	s_add_u32 s36, s25, s34
	s_addc_u32 s37, s26, s35
	s_add_u32 s34, s20, s34
	s_addc_u32 s35, s21, s35
	global_load_dword v11, v3, s[6:7]
	global_load_dword v9, v3, s[8:9]
	global_load_dword v7, v3, s[28:29]
	global_load_dword v5, v3, s[4:5]
	global_load_dword v18, v3, s[30:31]
	global_load_dword v20, v3, s[18:19]
	global_load_dword v16, v3, s[36:37]
	global_load_dword v17, v3, s[34:35]
	s_lshl_b64 s[4:5], s[16:17], 8
	v_lshl_add_u64 v[40:41], v[14:15], 0, s[4:5]
	s_or_b32 s4, s2, 2
	s_ashr_i32 s5, s4, 31
	s_lshl_b64 s[4:5], s[4:5], 5
	s_or_b32 s4, s4, s27
	s_lshl_b64 s[6:7], s[4:5], 2
	s_add_u32 s8, s25, s6
	s_addc_u32 s9, s26, s7
	s_add_u32 s6, s20, s6
	s_addc_u32 s7, s21, s7
	s_lshl_b64 s[4:5], s[4:5], 8
	v_lshl_add_u64 v[42:43], v[14:15], 0, s[4:5]
	s_or_b32 s4, s2, 3
	s_ashr_i32 s5, s4, 31
	s_lshl_b64 s[4:5], s[4:5], 5
	s_or_b32 s4, s4, s27
	s_lshl_b64 s[16:17], s[4:5], 2
	s_add_u32 s18, s25, s16
	s_addc_u32 s19, s26, s17
	s_add_u32 s16, s20, s16
	s_addc_u32 s17, s21, s17
	s_lshl_b64 s[4:5], s[4:5], 8
	v_lshl_add_u64 v[44:45], v[14:15], 0, s[4:5]
	s_or_b32 s4, s2, 4
	s_ashr_i32 s5, s4, 31
	s_lshl_b64 s[4:5], s[4:5], 5
	s_or_b32 s4, s4, s27
	s_lshl_b64 s[28:29], s[4:5], 2
	s_add_u32 s30, s25, s28
	s_addc_u32 s31, s26, s29
	s_add_u32 s28, s20, s28
	s_addc_u32 s29, s21, s29
	s_lshl_b64 s[4:5], s[4:5], 8
	v_lshl_add_u64 v[52:53], v[14:15], 0, s[4:5]
	s_or_b32 s4, s2, 5
	s_ashr_i32 s5, s4, 31
	s_lshl_b64 s[4:5], s[4:5], 5
	s_or_b32 s4, s4, s27
	s_lshl_b64 s[34:35], s[4:5], 2
	s_add_u32 s36, s25, s34
	s_addc_u32 s37, s26, s35
	s_add_u32 s34, s20, s34
	s_addc_u32 s35, s21, s35
	s_lshl_b64 s[4:5], s[4:5], 8
	v_lshl_add_u64 v[58:59], v[14:15], 0, s[4:5]
	s_or_b32 s4, s2, 6
	s_ashr_i32 s5, s4, 31
	s_lshl_b64 s[4:5], s[4:5], 5
	s_or_b32 s4, s4, s27
	v_lshlrev_b32_e32 v2, 16, v25
	global_load_ushort v107, v[28:29], off
	global_load_ushort v106, v[30:31], off
	global_load_ushort v108, v[34:35], off
	global_load_ushort v105, v[36:37], off
	global_load_dword v33, v[38:39], off
	global_load_dword v27, v[40:41], off
	global_load_dword v21, v[42:43], off
	global_load_dword v19, v[44:45], off
	s_nop 0
	global_load_dword v43, v3, s[8:9]
	global_load_dword v44, v3, s[6:7]
	global_load_dword v36, v3, s[18:19]
	global_load_dword v37, v3, s[16:17]
	global_load_dword v30, v3, s[30:31]
	global_load_dword v32, v3, s[28:29]
	global_load_dword v25, v3, s[36:37]
	global_load_dword v26, v3, s[34:35]
	s_lshl_b64 s[6:7], s[4:5], 2
	s_add_u32 s8, s25, s6
	s_addc_u32 s9, s26, s7
	s_add_u32 s6, s20, s6
	s_addc_u32 s7, s21, s7
	s_lshl_b64 s[4:5], s[4:5], 8
	v_lshl_add_u64 v[124:125], v[14:15], 0, s[4:5]
	s_or_b32 s4, s2, 7
	s_ashr_i32 s5, s4, 31
	s_lshl_b64 s[4:5], s[4:5], 5
	s_or_b32 s4, s4, s27
	s_lshl_b64 s[16:17], s[4:5], 2
	s_add_u32 s18, s25, s16
	s_addc_u32 s19, s26, s17
	s_add_u32 s16, s20, s16
	s_addc_u32 s17, s21, s17
	s_lshl_b64 s[4:5], s[4:5], 8
	v_lshl_add_u64 v[126:127], v[14:15], 0, s[4:5]
	s_or_b32 s4, s2, 8
	s_ashr_i32 s5, s4, 31
	s_lshl_b64 s[4:5], s[4:5], 5
	s_or_b32 s4, s4, s27
	s_lshl_b64 s[28:29], s[4:5], 2
	s_add_u32 s30, s25, s28
	s_addc_u32 s31, s26, s29
	s_add_u32 s28, s20, s28
	s_addc_u32 s29, s21, s29
	s_lshl_b64 s[4:5], s[4:5], 8
	v_lshl_add_u64 v[128:129], v[14:15], 0, s[4:5]
	s_or_b32 s4, s2, 9
	s_ashr_i32 s5, s4, 31
	s_lshl_b64 s[4:5], s[4:5], 5
	s_or_b32 s4, s4, s27
	s_lshl_b64 s[34:35], s[4:5], 2
	s_add_u32 s36, s25, s34
	s_addc_u32 s37, s26, s35
	s_add_u32 s34, s20, s34
	s_addc_u32 s35, s21, s35
	s_lshl_b64 s[4:5], s[4:5], 8
	v_lshl_add_u64 v[130:131], v[14:15], 0, s[4:5]
	s_or_b32 s4, s2, 10
	s_ashr_i32 s5, s4, 31
	s_lshl_b64 s[4:5], s[4:5], 5
	s_or_b32 s4, s4, s27
	global_load_dword v46, v3, s[8:9]
	global_load_dword v48, v3, s[6:7]
	global_load_dword v39, v3, s[18:19]
	global_load_dword v41, v3, s[16:17]
	global_load_dword v34, v3, s[30:31]
	global_load_dword v35, v3, s[28:29]
	global_load_dword v28, v3, s[36:37]
	global_load_dword v29, v3, s[34:35]
	s_lshl_b64 s[6:7], s[4:5], 2
	s_add_u32 s8, s25, s6
	s_addc_u32 s9, s26, s7
	s_add_u32 s6, s20, s6
	s_addc_u32 s7, s21, s7
	s_lshl_b64 s[4:5], s[4:5], 8
	v_lshl_add_u64 v[132:133], v[14:15], 0, s[4:5]
	s_or_b32 s4, s2, 11
	s_ashr_i32 s5, s4, 31
	s_lshl_b64 s[4:5], s[4:5], 5
	s_or_b32 s4, s4, s27
	s_lshl_b64 s[16:17], s[4:5], 2
	s_add_u32 s18, s25, s16
	s_addc_u32 s19, s26, s17
	s_add_u32 s16, s20, s16
	s_addc_u32 s17, s21, s17
	s_lshl_b64 s[4:5], s[4:5], 8
	v_lshl_add_u64 v[134:135], v[14:15], 0, s[4:5]
	s_or_b32 s4, s2, 12
	s_ashr_i32 s5, s4, 31
	s_lshl_b64 s[4:5], s[4:5], 5
	s_or_b32 s4, s4, s27
	s_lshl_b64 s[28:29], s[4:5], 2
	s_add_u32 s30, s25, s28
	s_addc_u32 s31, s26, s29
	s_add_u32 s28, s20, s28
	s_addc_u32 s29, s21, s29
	s_lshl_b64 s[4:5], s[4:5], 8
	global_load_dword v72, v[52:53], off
	global_load_dword v67, v[58:59], off
	global_load_dword v62, v[124:125], off
	global_load_dword v57, v[126:127], off
	global_load_dword v51, v[128:129], off
	global_load_dword v45, v[130:131], off
	global_load_dword v38, v[132:133], off
	global_load_dword v31, v[134:135], off
	v_lshl_add_u64 v[124:125], v[14:15], 0, s[4:5]
	s_or_b32 s4, s2, 13
	s_ashr_i32 s5, s4, 31
	s_lshl_b64 s[4:5], s[4:5], 5
	s_or_b32 s4, s4, s27
	s_lshl_b64 s[34:35], s[4:5], 2
	s_add_u32 s36, s25, s34
	s_addc_u32 s37, s26, s35
	s_add_u32 s34, s20, s34
	s_addc_u32 s35, s21, s35
	s_lshl_b64 s[4:5], s[4:5], 8
	v_lshl_add_u64 v[126:127], v[14:15], 0, s[4:5]
	s_or_b32 s4, s2, 14
	s_ashr_i32 s5, s4, 31
	s_lshl_b64 s[4:5], s[4:5], 5
	s_or_b32 s4, s4, s27
	global_load_dword v59, v3, s[8:9]
	global_load_dword v60, v3, s[6:7]
	global_load_dword v53, v3, s[18:19]
	global_load_dword v54, v3, s[16:17]
	global_load_dword v47, v3, s[30:31]
	global_load_dword v50, v3, s[28:29]
	global_load_dword v40, v3, s[36:37]
	global_load_dword v42, v3, s[34:35]
	s_lshl_b64 s[6:7], s[4:5], 2
	s_add_u32 s8, s25, s6
	s_addc_u32 s9, s26, s7
	s_add_u32 s16, s20, s6
	s_addc_u32 s17, s21, s7
	s_or_b32 s2, s2, 15
	s_ashr_i32 s3, s2, 31
	s_lshl_b64 s[2:3], s[2:3], 5
	s_lshl_b64 s[4:5], s[4:5], 8
	s_or_b32 s2, s2, s27
	v_lshl_add_u64 v[128:129], v[14:15], 0, s[4:5]
	s_lshl_b64 s[4:5], s[2:3], 2
	s_add_u32 s18, s25, s4
	s_addc_u32 s19, s26, s5
	s_add_u32 s20, s20, s4
	s_addc_u32 s21, s21, s5
	s_lshl_b64 s[2:3], s[2:3], 8
	v_lshl_add_u64 v[14:15], v[14:15], 0, s[2:3]
	global_load_dword v131, v3, s[0:1]
	global_load_dword v133, v3, s[14:15]
	global_load_dword v135, v3, s[12:13]
	global_load_dword v63, v[124:125], off
	global_load_dword v58, v[126:127], off
	global_load_dword v52, v[128:129], off
	global_load_dword v49, v[14:15], off
	v_mbcnt_hi_u32_b32 v14, -1, v232
	v_and_b32_e32 v15, 64, v14
	v_add_u32_e32 v15, 64, v15
	v_xor_b32_e32 v119, 1, v14
	v_cmp_lt_i32_e32 vcc, v119, v15
	v_mul_f32_e32 v123, v2, v103
	v_mul_f32_e32 v124, v2, v92
	v_cndmask_b32_e32 v119, v14, v119, vcc
	v_lshlrev_b32_e32 v150, 2, v119
	ds_bpermute_b32 v123, v150, v123
	v_xor_b32_e32 v119, 2, v14
	v_cmp_lt_i32_e32 vcc, v119, v15
	ds_bpermute_b32 v124, v150, v124
	s_ashr_i32 s0, s22, 3
	v_cndmask_b32_e32 v119, v14, v119, vcc
	v_lshlrev_b32_e32 v151, 2, v119
	s_waitcnt lgkmcnt(0)
	v_fmac_f32_e32 v123, v2, v103
	v_xor_b32_e32 v119, 4, v14
	v_cmp_lt_i32_e32 vcc, v119, v15
	s_waitcnt lgkmcnt(0)
	v_fmac_f32_e32 v124, v2, v92
	v_cndmask_b32_e32 v119, v14, v119, vcc
	v_lshlrev_b32_e32 v152, 2, v119
	s_waitcnt lgkmcnt(0)
	s_nop 1
	v_add_f32_dpp v103, v123, v123 quad_perm:[2,3,0,1] row_mask:0xf bank_mask:0xf
	v_xor_b32_e32 v119, 8, v14
	v_cmp_lt_i32_e32 vcc, v119, v15
	s_and_b32 s0, s0, -4
	s_addk_i32 s0, 0x4100
	v_cndmask_b32_e32 v119, v14, v119, vcc
	v_lshlrev_b32_e32 v153, 2, v119
	s_waitcnt lgkmcnt(0)
	s_nop 1
	v_add_f32_dpp v123, v103, v103 row_shl:4 row_mask:0xf bank_mask:0x5
	v_add_f32_dpp v123, v103, v103 row_shr:4 row_mask:0xf bank_mask:0xa
	v_mov_b32_e32 v103, v123
	v_xor_b32_e32 v119, 16, v14
	v_cmp_lt_i32_e32 vcc, v119, v15
	s_cmp_eq_u32 s10, 0
	s_cselect_b64 s[2:3], -1, 0
	v_cndmask_b32_e32 v119, v14, v119, vcc
	v_lshlrev_b32_e32 v154, 2, v119
	s_waitcnt lgkmcnt(0)
	s_nop 1
	v_add_f32_dpp v103, v103, v103 row_ror:8 row_mask:0xf bank_mask:0xf
	v_xor_b32_e32 v119, 32, v14
	v_cmp_lt_i32_e32 vcc, v119, v15
	s_cmp_lt_u32 s10, 2
	s_cselect_b64 s[6:7], -1, 0
	v_cndmask_b32_e32 v14, v14, v119, vcc
	v_lshlrev_b32_e32 v155, 2, v14
	s_waitcnt lgkmcnt(0)
	v_mov_b32_e32 v123, v103
	s_nop 1
	v_permlane16_swap_b32_e32 v103, v123
	v_add_f32_e32 v14, v103, v123
	v_mul_f32_e32 v103, v12, v2
	ds_bpermute_b32 v15, v155, v14
	ds_bpermute_b32 v103, v150, v103
	s_cmp_eq_u32 s10, 3
	v_mov_b32_e32 v123, 0xf149f2ca
	s_cselect_b64 s[4:5], -1, 0
	s_waitcnt lgkmcnt(0)
	v_add_f32_e32 v125, v14, v15
	s_nop 1
	v_add_f32_dpp v14, v124, v124 quad_perm:[2,3,0,1] row_mask:0xf bank_mask:0xf
	s_waitcnt lgkmcnt(0)
	v_fmac_f32_e32 v103, v12, v2
	v_mul_f32_e32 v92, v2, v117
	ds_bpermute_b32 v92, v150, v92
	s_ashr_i32 s1, s0, 31
	s_waitcnt lgkmcnt(0)
	s_nop 1
	v_add_f32_dpp v15, v14, v14 row_shl:4 row_mask:0xf bank_mask:0x5
	v_add_f32_dpp v15, v14, v14 row_shr:4 row_mask:0xf bank_mask:0xa
	v_mov_b32_e32 v14, v15
	s_waitcnt lgkmcnt(0)
	s_nop 1
	v_add_f32_dpp v12, v103, v103 quad_perm:[2,3,0,1] row_mask:0xf bank_mask:0xf
	s_waitcnt lgkmcnt(0)
	v_fmac_f32_e32 v92, v2, v117
	s_waitcnt lgkmcnt(0)
	s_nop 1
	v_add_f32_dpp v14, v14, v14 row_ror:8 row_mask:0xf bank_mask:0xf
	s_waitcnt lgkmcnt(0)
	s_nop 1
	v_add_f32_dpp v103, v12, v12 row_shl:4 row_mask:0xf bank_mask:0x5
	v_add_f32_dpp v103, v12, v12 row_shr:4 row_mask:0xf bank_mask:0xa
	s_waitcnt lgkmcnt(0)
	s_nop 1
	v_add_f32_dpp v12, v92, v92 quad_perm:[2,3,0,1] row_mask:0xf bank_mask:0xf
	ds_bpermute_b32 v2, v152, v12
	s_waitcnt lgkmcnt(0)
	v_mov_b32_e32 v15, v14
	s_nop 1
	v_permlane16_swap_b32_e32 v14, v15
	v_add_f32_e32 v14, v14, v15
	s_waitcnt lgkmcnt(0)
	v_pk_add_f32 v[12:13], v[12:13], v[2:3]
	ds_bpermute_b32 v130, v153, v12
	s_waitcnt lgkmcnt(0)
	s_nop 1
	v_add_f32_dpp v92, v103, v103 row_ror:8 row_mask:0xf bank_mask:0xf
	v_fmac_f32_e32 v125, 0xbfb8aa3b, v13
	s_waitcnt lgkmcnt(0)
	v_mov_b32_e32 v15, v14
	s_nop 1
	v_permlane32_swap_b32_e32 v14, v15
	v_add_f32_e32 v2, v14, v15
	s_waitcnt vmcnt(6) lgkmcnt(0)
	v_pk_add_f32 v[14:15], v[12:13], v[130:131]
	ds_bpermute_b32 v132, v154, v14
	s_waitcnt lgkmcnt(0)
	v_mov_b32_e32 v103, v92
	s_nop 1
	v_permlane16_swap_b32_e32 v92, v103
	v_add_f32_e32 v92, v92, v103
	v_fmac_f32_e32 v2, 0xbfb8aa3b, v15
	v_cndmask_b32_e64 v2, v2, v123, s[2:3]
	s_waitcnt vmcnt(5) lgkmcnt(0)
	v_pk_add_f32 v[12:13], v[14:15], v[132:133]
	ds_bpermute_b32 v134, v155, v12
	s_waitcnt lgkmcnt(0)
	v_mov_b32_e32 v103, v92
	s_nop 1
	v_permlane32_swap_b32_e32 v92, v103
	v_add_f32_e32 v92, v92, v103
	v_fmac_f32_e32 v92, 0xbfb8aa3b, v13
	v_cndmask_b32_e64 v124, v92, v123, s[6:7]
	global_load_dword v117, v3, s[8:9]
	global_load_dword v119, v3, s[16:17]
	global_load_dword v92, v3, s[18:19]
	global_load_dword v103, v3, s[20:21]
	s_waitcnt vmcnt(8) lgkmcnt(0)
	v_pk_add_f32 v[12:13], v[12:13], v[134:135]
	s_mov_b32 s16, 0xefa18f08
	v_fmac_f32_e32 v12, 0xbfb8aa3b, v13
	v_cndmask_b32_e64 v126, v123, v12, s[4:5]
	v_max_f32_e32 v12, v124, v126
	v_max3_f32 v12, v125, v2, v12
	v_max3_f32 v12, v12, v89, v86
	v_max3_f32 v12, v12, v80, v75
	v_max3_f32 v12, v12, v85, v78
	v_max3_f32 v12, v12, v73, v70
	v_max3_f32 v12, v12, v98, v95
	v_max3_f32 v12, v12, v90, v83
	v_max3_f32 v12, v12, v115, v112
	v_max3_f32 v127, v12, v109, v101
	v_sub_f32_e32 v12, v89, v127
	v_exp_f32_e32 v12, v12
	v_sub_f32_e32 v14, v86, v127
	v_exp_f32_e32 v14, v14
	v_cmp_lt_f32_e32 vcc, s16, v89
	v_fma_f32 v13, v93, v12, 0
	v_fma_f32 v12, v79, v12, 0
	v_cndmask_b32_e32 v13, 0, v13, vcc
	v_cndmask_b32_e32 v12, 0, v12, vcc
	v_mul_f32_e32 v15, v88, v14
	v_cmp_lt_f32_e32 vcc, s16, v86
	v_mul_f32_e32 v14, v74, v14
	v_sub_f32_e32 v2, v2, v127
	v_cndmask_b32_e32 v15, 0, v15, vcc
	v_add_f32_e32 v13, v15, v13
	v_sub_f32_e32 v15, v80, v127
	v_exp_f32_e32 v15, v15
	v_cndmask_b32_e32 v14, 0, v14, vcc
	v_add_f32_e32 v12, v14, v12
	v_cmp_lt_f32_e32 vcc, s16, v80
	v_mul_f32_e32 v14, v82, v15
	v_mul_f32_e32 v15, v69, v15
	v_cndmask_b32_e32 v14, 0, v14, vcc
	v_add_f32_e32 v13, v14, v13
	v_sub_f32_e32 v14, v75, v127
	v_exp_f32_e32 v14, v14
	v_cndmask_b32_e32 v15, 0, v15, vcc
	v_add_f32_e32 v12, v15, v12
	v_cmp_lt_f32_e32 vcc, s16, v75
	v_mul_f32_e32 v15, v77, v14
	v_mul_f32_e32 v14, v68, v14
	v_cndmask_b32_e32 v15, 0, v15, vcc
	v_add_f32_e32 v13, v15, v13
	v_sub_f32_e32 v15, v85, v127
	v_exp_f32_e32 v15, v15
	v_cndmask_b32_e32 v14, 0, v14, vcc
	v_add_f32_e32 v12, v14, v12
	v_cmp_lt_f32_e32 vcc, s16, v85
	v_mul_f32_e32 v14, v87, v15
	v_mul_f32_e32 v15, v66, v15
	v_cndmask_b32_e32 v14, 0, v14, vcc
	v_add_f32_e32 v13, v14, v13
	v_sub_f32_e32 v14, v78, v127
	v_exp_f32_e32 v14, v14
	v_cndmask_b32_e32 v15, 0, v15, vcc
	v_add_f32_e32 v12, v15, v12
	v_cmp_lt_f32_e32 vcc, s16, v78
	v_mul_f32_e32 v15, v81, v14
	v_mul_f32_e32 v14, v61, v14
	v_cndmask_b32_e32 v15, 0, v15, vcc
	v_add_f32_e32 v13, v15, v13
	v_sub_f32_e32 v15, v73, v127
	v_exp_f32_e32 v15, v15
	v_cndmask_b32_e32 v14, 0, v14, vcc
	v_add_f32_e32 v12, v14, v12
	v_cmp_lt_f32_e32 vcc, s16, v73
	v_mul_f32_e32 v14, v76, v15
	v_mul_f32_e32 v15, v120, v15
	v_cndmask_b32_e32 v14, 0, v14, vcc
	v_add_f32_e32 v13, v14, v13
	v_sub_f32_e32 v14, v70, v127
	v_exp_f32_e32 v14, v14
	v_cndmask_b32_e32 v15, 0, v15, vcc
	v_add_f32_e32 v12, v15, v12
	v_cmp_lt_f32_e32 vcc, s16, v70
	v_mul_f32_e32 v15, v71, v14
	v_mul_f32_e32 v14, v118, v14
	v_cndmask_b32_e32 v15, 0, v15, vcc
	v_add_f32_e32 v13, v15, v13
	v_sub_f32_e32 v15, v98, v127
	v_exp_f32_e32 v15, v15
	v_cndmask_b32_e32 v14, 0, v14, vcc
	v_add_f32_e32 v12, v14, v12
	v_cmp_lt_f32_e32 vcc, s16, v98
	v_mul_f32_e32 v14, v99, v15
	v_mul_f32_e32 v15, v114, v15
	v_cndmask_b32_e32 v14, 0, v14, vcc
	v_add_f32_e32 v13, v14, v13
	v_sub_f32_e32 v14, v95, v127
	v_exp_f32_e32 v14, v14
	v_cndmask_b32_e32 v15, 0, v15, vcc
	v_add_f32_e32 v12, v15, v12
	v_cmp_lt_f32_e32 vcc, s16, v95
	v_mul_f32_e32 v15, v96, v14
	v_mul_f32_e32 v14, v111, v14
	v_cndmask_b32_e32 v15, 0, v15, vcc
	v_add_f32_e32 v13, v15, v13
	v_sub_f32_e32 v15, v90, v127
	v_exp_f32_e32 v15, v15
	v_cndmask_b32_e32 v14, 0, v14, vcc
	v_add_f32_e32 v12, v14, v12
	v_cmp_lt_f32_e32 vcc, s16, v90
	v_mul_f32_e32 v14, v91, v15
	v_mul_f32_e32 v15, v104, v15
	v_cndmask_b32_e32 v14, 0, v14, vcc
	v_add_f32_e32 v13, v14, v13
	v_sub_f32_e32 v14, v83, v127
	v_exp_f32_e32 v14, v14
	v_cndmask_b32_e32 v15, 0, v15, vcc
	v_add_f32_e32 v12, v15, v12
	v_cmp_lt_f32_e32 vcc, s16, v83
	v_mul_f32_e32 v15, v84, v14
	v_mul_f32_e32 v14, v100, v14
	v_cndmask_b32_e32 v15, 0, v15, vcc
	v_add_f32_e32 v13, v15, v13
	v_sub_f32_e32 v15, v115, v127
	v_exp_f32_e32 v15, v15
	v_cndmask_b32_e32 v14, 0, v14, vcc
	v_add_f32_e32 v12, v14, v12
	v_cmp_lt_f32_e32 vcc, s16, v115
	v_mul_f32_e32 v14, v116, v15
	v_mul_f32_e32 v15, v97, v15
	v_cndmask_b32_e32 v14, 0, v14, vcc
	v_add_f32_e32 v13, v14, v13
	v_sub_f32_e32 v14, v112, v127
	v_exp_f32_e32 v14, v14
	v_cndmask_b32_e32 v15, 0, v15, vcc
	v_add_f32_e32 v12, v15, v12
	v_cmp_lt_f32_e32 vcc, s16, v112
	v_mul_f32_e32 v15, v113, v14
	v_mul_f32_e32 v14, v94, v14
	v_cndmask_b32_e32 v15, 0, v15, vcc
	v_add_f32_e32 v13, v15, v13
	v_sub_f32_e32 v15, v109, v127
	v_exp_f32_e32 v15, v15
	v_cndmask_b32_e32 v14, 0, v14, vcc
	v_add_f32_e32 v12, v14, v12
	v_cmp_lt_f32_e32 vcc, s16, v109
	v_mul_f32_e32 v14, v110, v15
	v_mul_f32_e32 v15, v122, v15
	v_cndmask_b32_e32 v14, 0, v14, vcc
	v_add_f32_e32 v13, v14, v13
	v_sub_f32_e32 v14, v101, v127
	v_exp_f32_e32 v14, v14
	v_cndmask_b32_e32 v15, 0, v15, vcc
	v_add_f32_e32 v15, v15, v12
	v_cmp_lt_f32_e32 vcc, s16, v101
	v_mul_f32_e32 v12, v102, v14
	v_mul_f32_e32 v14, v121, v14
	v_cndmask_b32_e32 v12, 0, v12, vcc
	v_add_f32_e32 v61, v12, v13
	v_sub_f32_e32 v12, v125, v127
	v_exp_f32_e32 v13, v12
	v_exp_f32_e32 v12, v2
	v_cndmask_b32_e32 v2, 0, v14, vcc
	v_add_f32_e32 v2, v2, v15
	v_add_f32_e32 v14, v13, v61
	v_add_f32_e32 v61, v12, v14
	v_lshlrev_b32_e32 v14, 16, v23
	v_lshlrev_b32_e32 v15, 16, v24
	v_pk_mul_f32 v[12:13], v[12:13], v[14:15]
	v_sub_f32_e32 v14, v124, v127
	v_exp_f32_e32 v15, v14
	v_sub_f32_e32 v14, v126, v127
	v_exp_f32_e32 v14, v14
	v_add_f32_e32 v2, v13, v2
	s_add_u32 s8, s72, 0x10000000
	v_add_f32_e32 v2, v12, v2
	v_add_f32_e32 v12, v15, v61
	s_addc_u32 s9, s73, 0
	s_or_b32 s0, s0, s10
	v_add_f32_e32 v23, v14, v12
	v_lshlrev_b32_e32 v13, 16, v22
	v_lshlrev_b32_e32 v12, 16, v6
	s_lshl_b64 s[0:1], s[0:1], 11
	v_pk_mul_f32 v[12:13], v[14:15], v[12:13]
	s_add_u32 s12, s8, s0
	v_add_f32_e32 v2, v13, v2
	s_addc_u32 s13, s9, s1
	s_lshl_b32 s0, s22, 4
	v_add_f32_e32 v2, v12, v2
	s_and_b32 s0, s0, 0x1c0
	s_lshl_b32 s17, s0, 1
	v_div_scale_f32 v6, s[0:1], v23, v23, v2
	v_rcp_f32_e32 v12, v6
	s_movk_i32 s18, 0x7fff
	s_add_u32 s0, s12, s17
	s_addc_u32 s1, s13, 0
	v_fma_f32 v13, -v6, v12, 1.0
	v_fmac_f32_e32 v12, v13, v12
	v_div_scale_f32 v13, vcc, v2, v23, v2
	v_mul_f32_e32 v14, v13, v12
	v_fma_f32 v15, -v6, v14, v13
	v_fmac_f32_e32 v14, v15, v12
	v_fma_f32 v6, -v6, v14, v13
	v_div_fmas_f32 v6, v6, v12, v14
	v_div_fixup_f32 v2, v6, v23, v2
	v_mul_f32_e32 v2, v2, v4
	v_bfe_u32 v4, v2, 16, 1
	v_add3_u32 v2, v2, v4, s18
	v_lshlrev_b32_e32 v22, 1, v1
	v_lshrrev_b32_e32 v2, 16, v2
	global_store_short v22, v2, s[0:1] sc1
	s_waitcnt vmcnt(0)
	v_cmp_eq_u32_e64 s[0:1], 0, v1
	s_and_saveexec_b64 s[12:13], s[0:1]
	s_cbranch_execz .LBB0_1471
	s_mov_b64 s[14:15], exec
	v_mbcnt_lo_u32_b32 v1, s14, 0
	v_mbcnt_hi_u32_b32 v1, s15, v1
	v_cmp_eq_u32_e32 vcc, 0, v1
	s_and_b64 s[20:21], exec, vcc
	s_mov_b64 exec, s[20:21]
	s_cbranch_execz .LBB0_1471
	s_ashr_i32 s19, s22, 2
	s_and_b32 s20, s19, 0xffffffc0
	s_ashr_i32 s21, s20, 31
	s_lshl_b64 s[20:21], s[20:21], 2
	s_add_u32 s20, s72, s20
	s_addc_u32 s21, s73, s21
	s_bcnt1_i32_b64 s14, s[14:15]
	v_mov_b32_e32 v1, 0xc000
	v_mov_b32_e32 v2, s14
	global_atomic_add v1, v2, s[20:21]
.LBB0_1471:
	s_or_b64 exec, exec, s[12:13]
	v_lshlrev_b32_e32 v1, 16, v64
	v_lshlrev_b32_e32 v2, 16, v65
	v_mul_f32_e32 v4, v1, v2
	ds_bpermute_b32 v4, v150, v4
	v_lshlrev_b32_e32 v6, 16, v56
	v_lshlrev_b32_e32 v14, 16, v8
	v_lshlrev_b32_e32 v8, 16, v107
	v_lshlrev_b32_e32 v15, 16, v55
	s_waitcnt lgkmcnt(0)
	v_fmac_f32_e32 v4, v1, v2
	v_mul_f32_e32 v24, v1, v6
	v_mul_f32_e32 v55, v1, v8
	ds_bpermute_b32 v24, v150, v24
	ds_bpermute_b32 v55, v150, v55
	s_waitcnt lgkmcnt(0)
	s_nop 1
	v_add_f32_dpp v2, v4, v4 quad_perm:[2,3,0,1] row_mask:0xf bank_mask:0xf
	v_lshlrev_b32_e32 v23, 16, v10
	v_lshlrev_b32_e32 v10, 16, v108
	v_mul_f32_e32 v56, v1, v10
	s_waitcnt lgkmcnt(0)
	v_fmac_f32_e32 v24, v1, v6
	s_waitcnt lgkmcnt(0)
	s_nop 1
	v_add_f32_dpp v4, v2, v2 row_shl:4 row_mask:0xf bank_mask:0x5
	v_add_f32_dpp v4, v2, v2 row_shr:4 row_mask:0xf bank_mask:0xa
	v_mov_b32_e32 v2, v4
	ds_bpermute_b32 v56, v150, v56
	v_fmac_f32_e32 v55, v1, v8
	s_waitcnt lgkmcnt(0)
	s_nop 1
	v_add_f32_dpp v2, v2, v2 row_ror:8 row_mask:0xf bank_mask:0xf
	s_waitcnt lgkmcnt(0)
	v_fmac_f32_e32 v56, v1, v10
	s_waitcnt lgkmcnt(0)
	s_nop 1
	v_add_f32_dpp v6, v24, v24 quad_perm:[2,3,0,1] row_mask:0xf bank_mask:0xf
	s_waitcnt lgkmcnt(0)
	s_nop 1
	v_add_f32_dpp v8, v55, v55 quad_perm:[2,3,0,1] row_mask:0xf bank_mask:0xf
	s_waitcnt lgkmcnt(0)
	v_mov_b32_e32 v4, v2
	s_nop 1
	v_permlane16_swap_b32_e32 v2, v4
	v_add_f32_e32 v4, v2, v4
	s_waitcnt lgkmcnt(0)
	s_nop 1
	v_add_f32_dpp v10, v56, v56 quad_perm:[2,3,0,1] row_mask:0xf bank_mask:0xf
	v_cmp_lt_f32_e32 vcc, s16, v18
	s_waitcnt lgkmcnt(0)
	s_nop 1
	v_add_f32_dpp v2, v6, v6 row_shl:4 row_mask:0xf bank_mask:0x5
	v_add_f32_dpp v2, v6, v6 row_shr:4 row_mask:0xf bank_mask:0xa
	v_mov_b32_e32 v6, v2
	s_waitcnt lgkmcnt(0)
	s_nop 1
	v_add_f32_dpp v55, v8, v8 row_shl:4 row_mask:0xf bank_mask:0x5
	v_add_f32_dpp v55, v8, v8 row_shr:4 row_mask:0xf bank_mask:0xa
	v_mov_b32_e32 v8, v55
	ds_bpermute_b32 v2, v152, v10
	s_waitcnt lgkmcnt(0)
	v_mov_b32_e32 v24, v4
	s_nop 1
	v_permlane32_swap_b32_e32 v4, v24
	v_add_f32_e32 v24, v4, v24
	v_lshlrev_b32_e32 v13, 16, v106
	s_waitcnt lgkmcnt(0)
	v_pk_add_f32 v[2:3], v[10:11], v[2:3]
	s_waitcnt lgkmcnt(0)
	s_nop 1
	v_add_f32_dpp v1, v6, v6 row_ror:8 row_mask:0xf bank_mask:0xf
	s_waitcnt lgkmcnt(0)
	s_nop 1
	v_add_f32_dpp v55, v8, v8 row_ror:8 row_mask:0xf bank_mask:0xf
	ds_bpermute_b32 v8, v153, v2
	v_fmac_f32_e32 v24, 0xbfb8aa3b, v3
	v_lshlrev_b32_e32 v12, 16, v105
	s_waitcnt lgkmcnt(0)
	v_pk_add_f32 v[8:9], v[2:3], v[8:9]
	s_waitcnt lgkmcnt(0)
	v_mov_b32_e32 v6, v1
	s_nop 1
	v_permlane16_swap_b32_e32 v1, v6
	v_add_f32_e32 v1, v1, v6
	ds_bpermute_b32 v6, v154, v8
	s_waitcnt lgkmcnt(0)
	v_mov_b32_e32 v56, v55
	s_nop 1
	v_permlane16_swap_b32_e32 v55, v56
	v_add_f32_e32 v11, v55, v56
	s_waitcnt lgkmcnt(0)
	v_pk_add_f32 v[2:3], v[8:9], v[6:7]
	ds_bpermute_b32 v4, v155, v2
	s_waitcnt lgkmcnt(0)
	v_mov_b32_e32 v10, v1
	s_nop 1
	v_permlane32_swap_b32_e32 v1, v10
	v_add_f32_e32 v1, v1, v10
	s_waitcnt lgkmcnt(0)
	v_mov_b32_e32 v55, v11
	s_nop 1
	v_permlane32_swap_b32_e32 v11, v55
	v_add_f32_e32 v10, v11, v55
	v_fmac_f32_e32 v10, 0xbfb8aa3b, v3
	v_fmac_f32_e32 v1, 0xbfb8aa3b, v9
	s_waitcnt lgkmcnt(0)
	v_pk_add_f32 v[2:3], v[2:3], v[4:5]
	v_cndmask_b32_e64 v6, v10, v123, s[6:7]
	v_fmac_f32_e32 v2, 0xbfb8aa3b, v3
	v_cndmask_b32_e64 v4, v123, v2, s[4:5]
	v_cndmask_b32_e64 v1, v1, v123, s[2:3]
	v_max_f32_e32 v2, v6, v4
	v_max3_f32 v2, v24, v1, v2
	v_max3_f32 v2, v2, v18, v16
	v_max3_f32 v2, v2, v43, v36
	v_max3_f32 v2, v2, v30, v25
	v_max3_f32 v2, v2, v46, v39
	v_max3_f32 v2, v2, v34, v28
	v_max3_f32 v2, v2, v59, v53
	v_max3_f32 v2, v2, v47, v40
	s_waitcnt vmcnt(2)
	v_max3_f32 v7, v2, v117, v92
	v_sub_f32_e32 v2, v18, v7
	v_exp_f32_e32 v2, v2
	v_sub_f32_e32 v5, v16, v7
	v_exp_f32_e32 v5, v5
	v_sub_f32_e32 v1, v1, v7
	v_fma_f32 v3, v20, v2, 0
	v_fma_f32 v2, v33, v2, 0
	v_cndmask_b32_e32 v3, 0, v3, vcc
	v_cndmask_b32_e32 v2, 0, v2, vcc
	v_mul_f32_e32 v8, v17, v5
	v_cmp_lt_f32_e32 vcc, s16, v16
	v_mul_f32_e32 v5, v27, v5
	v_sub_f32_e32 v4, v4, v7
	v_cndmask_b32_e32 v8, 0, v8, vcc
	v_add_f32_e32 v3, v8, v3
	v_sub_f32_e32 v8, v43, v7
	v_exp_f32_e32 v8, v8
	v_cndmask_b32_e32 v5, 0, v5, vcc
	v_add_f32_e32 v2, v5, v2
	v_cmp_lt_f32_e32 vcc, s16, v43
	v_mul_f32_e32 v5, v44, v8
	v_mul_f32_e32 v8, v21, v8
	v_cndmask_b32_e32 v5, 0, v5, vcc
	v_add_f32_e32 v3, v5, v3
	v_sub_f32_e32 v5, v36, v7
	v_exp_f32_e32 v5, v5
	v_cndmask_b32_e32 v8, 0, v8, vcc
	v_add_f32_e32 v2, v8, v2
	v_cmp_lt_f32_e32 vcc, s16, v36
	v_mul_f32_e32 v8, v37, v5
	v_mul_f32_e32 v5, v19, v5
	v_cndmask_b32_e32 v8, 0, v8, vcc
	v_add_f32_e32 v3, v8, v3
	v_sub_f32_e32 v8, v30, v7
	v_exp_f32_e32 v8, v8
	v_cndmask_b32_e32 v5, 0, v5, vcc
	v_add_f32_e32 v2, v5, v2
	v_cmp_lt_f32_e32 vcc, s16, v30
	v_mul_f32_e32 v5, v32, v8
	v_mul_f32_e32 v8, v72, v8
	v_cndmask_b32_e32 v5, 0, v5, vcc
	v_add_f32_e32 v3, v5, v3
	v_sub_f32_e32 v5, v25, v7
	v_exp_f32_e32 v5, v5
	v_cndmask_b32_e32 v8, 0, v8, vcc
	v_add_f32_e32 v2, v8, v2
	v_cmp_lt_f32_e32 vcc, s16, v25
	v_mul_f32_e32 v8, v26, v5
	v_mul_f32_e32 v5, v67, v5
	v_cndmask_b32_e32 v8, 0, v8, vcc
	v_add_f32_e32 v3, v8, v3
	v_sub_f32_e32 v8, v46, v7
	v_exp_f32_e32 v8, v8
	v_cndmask_b32_e32 v5, 0, v5, vcc
	v_add_f32_e32 v2, v5, v2
	v_cmp_lt_f32_e32 vcc, s16, v46
	v_mul_f32_e32 v5, v48, v8
	v_mul_f32_e32 v8, v62, v8
	v_cndmask_b32_e32 v5, 0, v5, vcc
	v_add_f32_e32 v3, v5, v3
	v_sub_f32_e32 v5, v39, v7
	v_exp_f32_e32 v5, v5
	v_cndmask_b32_e32 v8, 0, v8, vcc
	v_add_f32_e32 v2, v8, v2
	v_cmp_lt_f32_e32 vcc, s16, v39
	v_mul_f32_e32 v8, v41, v5
	v_mul_f32_e32 v5, v57, v5
	v_cndmask_b32_e32 v8, 0, v8, vcc
	v_add_f32_e32 v3, v8, v3
	v_sub_f32_e32 v8, v34, v7
	v_exp_f32_e32 v8, v8
	v_cndmask_b32_e32 v5, 0, v5, vcc
	v_add_f32_e32 v2, v5, v2
	v_cmp_lt_f32_e32 vcc, s16, v34
	v_mul_f32_e32 v5, v35, v8
	v_mul_f32_e32 v8, v51, v8
	v_cndmask_b32_e32 v5, 0, v5, vcc
	v_add_f32_e32 v3, v5, v3
	v_sub_f32_e32 v5, v28, v7
	v_exp_f32_e32 v5, v5
	v_cndmask_b32_e32 v8, 0, v8, vcc
	v_add_f32_e32 v2, v8, v2
	v_cmp_lt_f32_e32 vcc, s16, v28
	v_mul_f32_e32 v8, v29, v5
	v_mul_f32_e32 v5, v45, v5
	v_cndmask_b32_e32 v8, 0, v8, vcc
	v_add_f32_e32 v3, v8, v3
	v_sub_f32_e32 v8, v59, v7
	v_exp_f32_e32 v8, v8
	v_cndmask_b32_e32 v5, 0, v5, vcc
	v_add_f32_e32 v2, v5, v2
	v_cmp_lt_f32_e32 vcc, s16, v59
	v_mul_f32_e32 v5, v60, v8
	v_mul_f32_e32 v8, v38, v8
	v_cndmask_b32_e32 v5, 0, v5, vcc
	v_add_f32_e32 v3, v5, v3
	v_sub_f32_e32 v5, v53, v7
	v_exp_f32_e32 v5, v5
	v_cndmask_b32_e32 v8, 0, v8, vcc
	v_add_f32_e32 v2, v8, v2
	v_cmp_lt_f32_e32 vcc, s16, v53
	v_mul_f32_e32 v8, v54, v5
	v_mul_f32_e32 v5, v31, v5
	v_cndmask_b32_e32 v8, 0, v8, vcc
	v_add_f32_e32 v3, v8, v3
	v_sub_f32_e32 v8, v47, v7
	v_exp_f32_e32 v8, v8
	v_cndmask_b32_e32 v5, 0, v5, vcc
	v_add_f32_e32 v2, v5, v2
	v_cmp_lt_f32_e32 vcc, s16, v47
	v_mul_f32_e32 v5, v50, v8
	v_mul_f32_e32 v8, v63, v8
	v_cndmask_b32_e32 v5, 0, v5, vcc
	v_add_f32_e32 v3, v5, v3
	v_sub_f32_e32 v5, v40, v7
	v_exp_f32_e32 v5, v5
	v_cndmask_b32_e32 v8, 0, v8, vcc
	v_add_f32_e32 v2, v8, v2
	v_cmp_lt_f32_e32 vcc, s16, v40
	v_mul_f32_e32 v8, v42, v5
	v_mul_f32_e32 v5, v58, v5
	v_cndmask_b32_e32 v8, 0, v8, vcc
	v_add_f32_e32 v3, v8, v3
	v_sub_f32_e32 v8, v117, v7
	v_exp_f32_e32 v8, v8
	v_cndmask_b32_e32 v5, 0, v5, vcc
	v_add_f32_e32 v2, v5, v2
	v_cmp_lt_f32_e32 vcc, s16, v117
	v_mul_f32_e32 v5, v119, v8
	v_mul_f32_e32 v8, v52, v8
	v_cndmask_b32_e32 v5, 0, v5, vcc
	v_add_f32_e32 v3, v5, v3
	v_sub_f32_e32 v5, v92, v7
	v_exp_f32_e32 v5, v5
	v_cndmask_b32_e32 v8, 0, v8, vcc
	v_add_f32_e32 v8, v8, v2
	v_cmp_lt_f32_e32 vcc, s16, v92
	s_waitcnt vmcnt(1)
	v_mul_f32_e32 v2, v103, v5
	v_mul_f32_e32 v5, v49, v5
	v_cndmask_b32_e32 v2, 0, v2, vcc
	v_add_f32_e32 v9, v2, v3
	v_sub_f32_e32 v2, v24, v7
	v_exp_f32_e32 v3, v2
	v_exp_f32_e32 v2, v1
	v_cndmask_b32_e32 v1, 0, v5, vcc
	v_add_f32_e32 v1, v1, v8
	v_add_f32_e32 v5, v3, v9
	v_add_f32_e32 v8, v2, v5
	v_sub_f32_e32 v5, v6, v7
	v_exp_f32_e32 v5, v5
	v_exp_f32_e32 v4, v4
	v_pk_mul_f32 v[2:3], v[2:3], v[14:15]
	s_ashr_i32 s2, s24, 3
	v_add_f32_e32 v1, v3, v1
	v_add_f32_e32 v1, v2, v1
	v_add_f32_e32 v2, v5, v8
	v_add_f32_e32 v6, v4, v2
	v_pk_mul_f32 v[2:3], v[4:5], v[12:13]
	s_and_b32 s2, s2, -4
	v_add_f32_e32 v1, v3, v1
	v_add_f32_e32 v1, v2, v1
	v_div_scale_f32 v2, s[4:5], v6, v6, v1
	v_rcp_f32_e32 v3, v2
	s_addk_i32 s2, 0x4100
	s_ashr_i32 s3, s2, 31
	s_or_b64 s[2:3], s[2:3], s[10:11]
	v_fma_f32 v4, -v2, v3, 1.0
	v_fmac_f32_e32 v3, v4, v3
	v_div_scale_f32 v4, vcc, v1, v6, v1
	v_mul_f32_e32 v5, v4, v3
	v_fma_f32 v7, -v2, v5, v4
	v_fmac_f32_e32 v5, v7, v3
	v_fma_f32 v2, -v2, v5, v4
	v_div_fmas_f32 v2, v2, v3, v5
	s_lshl_b64 s[2:3], s[2:3], 11
	v_div_fixup_f32 v1, v2, v6, v1
	s_add_u32 s2, s8, s2
	v_mul_f32_e32 v1, v1, v23
	s_addc_u32 s3, s9, s3
	v_bfe_u32 v2, v1, 16, 1
	s_add_u32 s2, s2, s17
	v_add3_u32 v1, v1, v2, s18
	s_addc_u32 s3, s3, 0
	v_lshrrev_b32_e32 v1, 16, v1
	global_store_short v22, v1, s[2:3] sc1
	s_waitcnt vmcnt(0)
	s_and_saveexec_b64 s[2:3], s[0:1]
	s_cbranch_execz .LBB0_1474
	s_mov_b64 s[0:1], exec
	v_mbcnt_lo_u32_b32 v1, s0, 0
	v_mbcnt_hi_u32_b32 v1, s1, v1
	v_cmp_eq_u32_e32 vcc, 0, v1
	s_and_b64 s[4:5], exec, vcc
	s_mov_b64 exec, s[4:5]
	s_cbranch_execz .LBB0_1474
	s_ashr_i32 s4, s24, 2
	s_andn2_b32 s4, s4, 63
	s_ashr_i32 s5, s4, 31
	s_lshl_b64 s[4:5], s[4:5], 2
	s_add_u32 s4, s72, s4
	s_addc_u32 s5, s73, s5
	s_bcnt1_i32_b64 s0, s[0:1]
	v_mov_b32_e32 v1, 0xc000
	v_mov_b32_e32 v2, s0
	global_atomic_add v1, v2, s[4:5]

.LBB0_1477:
	global_load_dword v4, v3, s[0:1] sc1
	s_mov_b64 s[2:3], -1
	s_waitcnt vmcnt(0)
	v_readfirstlane_b32 s4, v4
	s_cmpk_gt_u32 s4, 0xff
	s_mov_b64 s[4:5], -1
	s_cbranch_scc1 .LBB0_1476
	s_sleep 2
	global_load_dword v4, v3, s[0:1] sc1
	s_waitcnt vmcnt(0)
	v_readfirstlane_b32 s4, v4
	s_cmpk_lt_u32 s4, 0x100
	s_mov_b64 s[4:5], -1
	s_cbranch_scc0 .LBB0_1476
	s_sleep 2
	global_load_dword v4, v3, s[0:1] sc1
	s_waitcnt vmcnt(0)
	v_readfirstlane_b32 s4, v4
	s_cmpk_lt_u32 s4, 0x100
	s_mov_b64 s[4:5], -1
	s_cbranch_scc0 .LBB0_1476
	s_sleep 2
	global_load_dword v4, v3, s[0:1] sc1
	s_waitcnt vmcnt(0)
	v_readfirstlane_b32 s4, v4
	s_cmpk_lt_u32 s4, 0x100
	s_mov_b64 s[4:5], -1
	s_cbranch_scc0 .LBB0_1476
	s_sleep 2
	global_load_dword v4, v3, s[0:1] sc1
	s_waitcnt vmcnt(0)
	v_readfirstlane_b32 s4, v4
	s_cmpk_lt_u32 s4, 0x100
	s_mov_b64 s[4:5], -1
	s_cbranch_scc0 .LBB0_1476
	s_add_i32 s11, s11, -5
	s_cmp_eq_u32 s11, 0
	s_mov_b64 s[2:3], 0
	s_cselect_b64 s[4:5], -1, 0
	s_sleep 2
	s_branch .LBB0_1476
	s_nop 0
	s_nop 0
	s_nop 0
	s_nop 0
	s_nop 0
	s_nop 0
	s_nop 0
	s_nop 0
	s_nop 0
	s_nop 0
	s_nop 0
	s_nop 0
	s_nop 0
	s_nop 0
	s_nop 0
	s_nop 0
	s_nop 0
	s_nop 0
	s_nop 0
	s_nop 0
	s_nop 0
	s_nop 0
	s_nop 0
	s_nop 0
	s_nop 0
	s_nop 0
	s_nop 0
	s_nop 0
	s_nop 0
	s_nop 0
	s_nop 0
	s_nop 0
	s_nop 0
	s_nop 0
	s_nop 0
	s_nop 0
